# GEMM epilogues of in1 / w1 (both layers): pair-packed dword stores with scalar-base addressing instead of 2-byte stores with 64-bit per-element address math
# speedup vs baseline: 1.0059x; 1.0059x over previous
; __device__ __forceinline__ bf16_t f2bf(float x) { return (bf16_t)(cvtpk(x, 0.f) & 0xffffu); }
; __device__ __forceinline__ int crow(int r, int hi) { return (r & 3) + 8 * (r >> 2) + 4 * hi; }
; template <class Epi>
; __device__ __forceinline__ void gemm8p(const bf16_t* __restrict__ A, int lda, const bf16_t* __restrict__ Bt, int ldb, int K,
;                                        LP lds, const Epi& epi, bool pre = false, const bf16_t* An = nullptr, const bf16_t* Bn = nullptr) {
;     ...
;   int e_rr = wr * 64, e_cc = wc * 32 + r32, e_hi = hi;
;   asm volatile("" : "+v"(e_rr), "+v"(e_cc), "+v"(e_hi));
; #pragma unroll
;   for (int a = 0; a < 2; ++a)
; #pragma unroll
;     for (int b = 0; b < 2; ++b)
; #pragma unroll
;       for (int m = 0; m < 2; ++m) { __builtin_amdgcn_sched_barrier(0); epi(a * 128 + e_rr + m * 32, b * 128 + e_cc, e_hi, acc[a][b][m]); }
; __device__ __forceinline__ void phase_gemm_in1(const Params& p, LP lds) {
;     ...
;     gemm8p(H + (size_t)row0 * 1024, 1024, WT + (size_t)col0 * 1024, 1024, 1024, lds, [&](int rr, int cc, int hi, f32x16 v) __attribute__((always_inline)) {
;       const int col = col0 + cc;
; #pragma unroll
;       for (int r = 0; r < 16; ++r) { const size_t row = row0 + rr + crow(r, hi); Q[row * 1536 + col] = f2bf(v[r]); }
;     }, pre, hasn ? H + (size_t)rown * 1024 : nullptr, hasn ? WT + (size_t)coln * 1024 : nullptr);
.LBB0_1947:
	s_nop 0
	s_mul_i32 s100, s64, 0xc00
	s_lshl_b32 s101, s66, 1
	s_add_u32 s100, s100, s101
	s_add_u32 s98, s4, s100
	s_addc_u32 s99, s5, 0
	v_lshl_add_u32 v130, v150, 2, v149
	v_and_b32_e32 v131, 1, v151
	v_add_u32_e32 v130, v130, v131
	v_sub_u32_e32 v132, v151, v131
	v_mul_u32_u24_e32 v130, 0xc00, v130
	v_lshl_add_u32 v130, v132, 1, v130
	v_sub_u32_e32 v132, 0, v131
	v_and_b32_e32 v132, 0x6060606, v132
	v_xor_b32_e32 v131, 0x5040100, v132
	v_cvt_pk_bf16_f32 v133, v112, v113
	v_cvt_pk_bf16_f32 v134, v80, v81
	s_nop 1
	v_mov_b32_dpp v135, v133 quad_perm:[1,0,3,2] row_mask:0xf bank_mask:0xf
	v_mov_b32_dpp v136, v134 quad_perm:[1,0,3,2] row_mask:0xf bank_mask:0xf
	v_perm_b32 v137, v135, v133, v131
	v_perm_b32 v138, v136, v134, v131
	global_store_dword v130, v137, s[98:99]
	global_store_dword v130, v138, s[98:99] offset:256
	v_cvt_pk_bf16_f32 v139, v114, v115
	v_cvt_pk_bf16_f32 v140, v82, v83
	s_add_u32 s98, s98, 0x1800
	s_addc_u32 s99, s99, 0
	v_mov_b32_dpp v141, v139 quad_perm:[1,0,3,2] row_mask:0xf bank_mask:0xf
	v_mov_b32_dpp v142, v140 quad_perm:[1,0,3,2] row_mask:0xf bank_mask:0xf
	v_perm_b32 v143, v141, v139, v131
	v_perm_b32 v144, v142, v140, v131
	global_store_dword v130, v143, s[98:99]
	global_store_dword v130, v144, s[98:99] offset:256
	v_cvt_pk_bf16_f32 v133, v116, v117
	v_cvt_pk_bf16_f32 v134, v84, v85
	s_add_u32 s98, s98, 0x4800
	s_addc_u32 s99, s99, 0
	v_mov_b32_dpp v135, v133 quad_perm:[1,0,3,2] row_mask:0xf bank_mask:0xf
	v_mov_b32_dpp v136, v134 quad_perm:[1,0,3,2] row_mask:0xf bank_mask:0xf
	v_perm_b32 v137, v135, v133, v131
	v_perm_b32 v138, v136, v134, v131
	global_store_dword v130, v137, s[98:99]
	global_store_dword v130, v138, s[98:99] offset:256
	v_cvt_pk_bf16_f32 v139, v118, v119
	v_cvt_pk_bf16_f32 v140, v86, v87
	s_add_u32 s98, s98, 0x1800
	s_addc_u32 s99, s99, 0
	v_mov_b32_dpp v141, v139 quad_perm:[1,0,3,2] row_mask:0xf bank_mask:0xf
	v_mov_b32_dpp v142, v140 quad_perm:[1,0,3,2] row_mask:0xf bank_mask:0xf
	v_perm_b32 v143, v141, v139, v131
	v_perm_b32 v144, v142, v140, v131
	global_store_dword v130, v143, s[98:99]
	global_store_dword v130, v144, s[98:99] offset:256
	v_cvt_pk_bf16_f32 v133, v120, v121
	v_cvt_pk_bf16_f32 v134, v88, v89
	s_add_u32 s98, s98, 0x4800
	s_addc_u32 s99, s99, 0
	v_mov_b32_dpp v135, v133 quad_perm:[1,0,3,2] row_mask:0xf bank_mask:0xf
	v_mov_b32_dpp v136, v134 quad_perm:[1,0,3,2] row_mask:0xf bank_mask:0xf
	v_perm_b32 v137, v135, v133, v131
	v_perm_b32 v138, v136, v134, v131
	global_store_dword v130, v137, s[98:99]
	global_store_dword v130, v138, s[98:99] offset:256
	v_cvt_pk_bf16_f32 v139, v122, v123
	v_cvt_pk_bf16_f32 v140, v90, v91
	s_add_u32 s98, s98, 0x1800
	s_addc_u32 s99, s99, 0
	v_mov_b32_dpp v141, v139 quad_perm:[1,0,3,2] row_mask:0xf bank_mask:0xf
	v_mov_b32_dpp v142, v140 quad_perm:[1,0,3,2] row_mask:0xf bank_mask:0xf
	v_perm_b32 v143, v141, v139, v131
	v_perm_b32 v144, v142, v140, v131
	global_store_dword v130, v143, s[98:99]
	global_store_dword v130, v144, s[98:99] offset:256
	v_cvt_pk_bf16_f32 v133, v124, v125
	v_cvt_pk_bf16_f32 v134, v92, v93
	s_add_u32 s98, s98, 0x4800
	s_addc_u32 s99, s99, 0
	v_mov_b32_dpp v135, v133 quad_perm:[1,0,3,2] row_mask:0xf bank_mask:0xf
	v_mov_b32_dpp v136, v134 quad_perm:[1,0,3,2] row_mask:0xf bank_mask:0xf
	v_perm_b32 v137, v135, v133, v131
	v_perm_b32 v138, v136, v134, v131
	global_store_dword v130, v137, s[98:99]
	global_store_dword v130, v138, s[98:99] offset:256
	v_cvt_pk_bf16_f32 v139, v126, v127
	v_cvt_pk_bf16_f32 v140, v94, v95
	s_add_u32 s98, s98, 0x1800
	s_addc_u32 s99, s99, 0
	v_mov_b32_dpp v141, v139 quad_perm:[1,0,3,2] row_mask:0xf bank_mask:0xf
	v_mov_b32_dpp v142, v140 quad_perm:[1,0,3,2] row_mask:0xf bank_mask:0xf
	v_perm_b32 v143, v141, v139, v131
	v_perm_b32 v144, v142, v140, v131
	global_store_dword v130, v143, s[98:99]
	global_store_dword v130, v144, s[98:99] offset:256
	v_cvt_pk_bf16_f32 v133, v96, v97
	v_cvt_pk_bf16_f32 v134, v64, v65
	s_add_u32 s98, s98, 0x4800
	s_addc_u32 s99, s99, 0
	v_mov_b32_dpp v135, v133 quad_perm:[1,0,3,2] row_mask:0xf bank_mask:0xf
	v_mov_b32_dpp v136, v134 quad_perm:[1,0,3,2] row_mask:0xf bank_mask:0xf
	v_perm_b32 v137, v135, v133, v131
	v_perm_b32 v138, v136, v134, v131
	global_store_dword v130, v137, s[98:99]
	global_store_dword v130, v138, s[98:99] offset:256
	v_cvt_pk_bf16_f32 v139, v98, v99
	v_cvt_pk_bf16_f32 v140, v66, v67
	s_add_u32 s98, s98, 0x1800
	s_addc_u32 s99, s99, 0
	v_mov_b32_dpp v141, v139 quad_perm:[1,0,3,2] row_mask:0xf bank_mask:0xf
	v_mov_b32_dpp v142, v140 quad_perm:[1,0,3,2] row_mask:0xf bank_mask:0xf
	v_perm_b32 v143, v141, v139, v131
	v_perm_b32 v144, v142, v140, v131
	global_store_dword v130, v143, s[98:99]
	global_store_dword v130, v144, s[98:99] offset:256
	v_cvt_pk_bf16_f32 v133, v100, v101
	v_cvt_pk_bf16_f32 v134, v68, v69
	s_add_u32 s98, s98, 0x4800
	s_addc_u32 s99, s99, 0
	v_mov_b32_dpp v135, v133 quad_perm:[1,0,3,2] row_mask:0xf bank_mask:0xf
	v_mov_b32_dpp v136, v134 quad_perm:[1,0,3,2] row_mask:0xf bank_mask:0xf
	v_perm_b32 v137, v135, v133, v131
	v_perm_b32 v138, v136, v134, v131
	global_store_dword v130, v137, s[98:99]
	global_store_dword v130, v138, s[98:99] offset:256
	v_cvt_pk_bf16_f32 v139, v102, v103
	v_cvt_pk_bf16_f32 v140, v70, v71
	s_add_u32 s98, s98, 0x1800
	s_addc_u32 s99, s99, 0
	v_mov_b32_dpp v141, v139 quad_perm:[1,0,3,2] row_mask:0xf bank_mask:0xf
	v_mov_b32_dpp v142, v140 quad_perm:[1,0,3,2] row_mask:0xf bank_mask:0xf
	v_perm_b32 v143, v141, v139, v131
	v_perm_b32 v144, v142, v140, v131
	global_store_dword v130, v143, s[98:99]
	global_store_dword v130, v144, s[98:99] offset:256
	v_cvt_pk_bf16_f32 v133, v104, v105
	v_cvt_pk_bf16_f32 v134, v72, v73
; __device__ __forceinline__ bf16_t f2bf(float x) { return (bf16_t)(cvtpk(x, 0.f) & 0xffffu); }
; __device__ __forceinline__ int crow(int r, int hi) { return (r & 3) + 8 * (r >> 2) + 4 * hi; }
; template <class Epi>
; __device__ __forceinline__ void gemm8p(const bf16_t* __restrict__ A, int lda, const bf16_t* __restrict__ Bt, int ldb, int K,
;                                        LP lds, const Epi& epi, bool pre = false, const bf16_t* An = nullptr, const bf16_t* Bn = nullptr) {
;     ...
;   int e_rr = wr * 64, e_cc = wc * 32 + r32, e_hi = hi;
;   asm volatile("" : "+v"(e_rr), "+v"(e_cc), "+v"(e_hi));
; #pragma unroll
;   for (int a = 0; a < 2; ++a)
; #pragma unroll
;     for (int b = 0; b < 2; ++b)
; #pragma unroll
;       for (int m = 0; m < 2; ++m) { __builtin_amdgcn_sched_barrier(0); epi(a * 128 + e_rr + m * 32, b * 128 + e_cc, e_hi, acc[a][b][m]); }
; __device__ __forceinline__ void phase_gemm_in1(const Params& p, LP lds) {
;     ...
;     gemm8p(H + (size_t)row0 * 1024, 1024, WT + (size_t)col0 * 1024, 1024, 1024, lds, [&](int rr, int cc, int hi, f32x16 v) __attribute__((always_inline)) {
;       const int col = col0 + cc;
; #pragma unroll
;       for (int r = 0; r < 16; ++r) { const size_t row = row0 + rr + crow(r, hi); Q[row * 1536 + col] = f2bf(v[r]); }
;     }, pre, hasn ? H + (size_t)rown * 1024 : nullptr, hasn ? WT + (size_t)coln * 1024 : nullptr);
	s_add_u32 s98, s98, 0x4800
	s_addc_u32 s99, s99, 0
	v_mov_b32_dpp v135, v133 quad_perm:[1,0,3,2] row_mask:0xf bank_mask:0xf
	v_mov_b32_dpp v136, v134 quad_perm:[1,0,3,2] row_mask:0xf bank_mask:0xf
	v_perm_b32 v137, v135, v133, v131
	v_perm_b32 v138, v136, v134, v131
	global_store_dword v130, v137, s[98:99]
	global_store_dword v130, v138, s[98:99] offset:256
	v_cvt_pk_bf16_f32 v139, v106, v107
	v_cvt_pk_bf16_f32 v140, v74, v75
	s_add_u32 s98, s98, 0x1800
	s_addc_u32 s99, s99, 0
	v_mov_b32_dpp v141, v139 quad_perm:[1,0,3,2] row_mask:0xf bank_mask:0xf
	v_mov_b32_dpp v142, v140 quad_perm:[1,0,3,2] row_mask:0xf bank_mask:0xf
	v_perm_b32 v143, v141, v139, v131
	v_perm_b32 v144, v142, v140, v131
	global_store_dword v130, v143, s[98:99]
	global_store_dword v130, v144, s[98:99] offset:256
	v_cvt_pk_bf16_f32 v133, v108, v109
	v_cvt_pk_bf16_f32 v134, v76, v77
	s_add_u32 s98, s98, 0x4800
	s_addc_u32 s99, s99, 0
	v_mov_b32_dpp v135, v133 quad_perm:[1,0,3,2] row_mask:0xf bank_mask:0xf
	v_mov_b32_dpp v136, v134 quad_perm:[1,0,3,2] row_mask:0xf bank_mask:0xf
	v_perm_b32 v137, v135, v133, v131
	v_perm_b32 v138, v136, v134, v131
	global_store_dword v130, v137, s[98:99]
	global_store_dword v130, v138, s[98:99] offset:256
	v_cvt_pk_bf16_f32 v139, v110, v111
	v_cvt_pk_bf16_f32 v140, v78, v79
	s_add_u32 s98, s98, 0x1800
	s_addc_u32 s99, s99, 0
	v_mov_b32_dpp v141, v139 quad_perm:[1,0,3,2] row_mask:0xf bank_mask:0xf
	v_mov_b32_dpp v142, v140 quad_perm:[1,0,3,2] row_mask:0xf bank_mask:0xf
	v_perm_b32 v143, v141, v139, v131
	v_perm_b32 v144, v142, v140, v131
	global_store_dword v130, v143, s[98:99]
	global_store_dword v130, v144, s[98:99] offset:256
	v_cvt_pk_bf16_f32 v133, v48, v49
	v_cvt_pk_bf16_f32 v134, v16, v17
	s_add_u32 s98, s98, 0x34800
	s_addc_u32 s99, s99, 0
	v_mov_b32_dpp v135, v133 quad_perm:[1,0,3,2] row_mask:0xf bank_mask:0xf
	v_mov_b32_dpp v136, v134 quad_perm:[1,0,3,2] row_mask:0xf bank_mask:0xf
	v_perm_b32 v137, v135, v133, v131
	v_perm_b32 v138, v136, v134, v131
	global_store_dword v130, v137, s[98:99]
	global_store_dword v130, v138, s[98:99] offset:256
	v_cvt_pk_bf16_f32 v139, v50, v51
	v_cvt_pk_bf16_f32 v140, v18, v19
	s_add_u32 s98, s98, 0x1800
	s_addc_u32 s99, s99, 0
	v_mov_b32_dpp v141, v139 quad_perm:[1,0,3,2] row_mask:0xf bank_mask:0xf
	v_mov_b32_dpp v142, v140 quad_perm:[1,0,3,2] row_mask:0xf bank_mask:0xf
	v_perm_b32 v143, v141, v139, v131
	v_perm_b32 v144, v142, v140, v131
	global_store_dword v130, v143, s[98:99]
	global_store_dword v130, v144, s[98:99] offset:256
	v_cvt_pk_bf16_f32 v133, v52, v53
	v_cvt_pk_bf16_f32 v134, v20, v21
	s_add_u32 s98, s98, 0x4800
	s_addc_u32 s99, s99, 0
	v_mov_b32_dpp v135, v133 quad_perm:[1,0,3,2] row_mask:0xf bank_mask:0xf
	v_mov_b32_dpp v136, v134 quad_perm:[1,0,3,2] row_mask:0xf bank_mask:0xf
	v_perm_b32 v137, v135, v133, v131
	v_perm_b32 v138, v136, v134, v131
	global_store_dword v130, v137, s[98:99]
	global_store_dword v130, v138, s[98:99] offset:256
	v_cvt_pk_bf16_f32 v139, v54, v55
	v_cvt_pk_bf16_f32 v140, v22, v23
	s_add_u32 s98, s98, 0x1800
	s_addc_u32 s99, s99, 0
	v_mov_b32_dpp v141, v139 quad_perm:[1,0,3,2] row_mask:0xf bank_mask:0xf
	v_mov_b32_dpp v142, v140 quad_perm:[1,0,3,2] row_mask:0xf bank_mask:0xf
	v_perm_b32 v143, v141, v139, v131
	v_perm_b32 v144, v142, v140, v131
	global_store_dword v130, v143, s[98:99]
	global_store_dword v130, v144, s[98:99] offset:256
	v_cvt_pk_bf16_f32 v133, v56, v57
	v_cvt_pk_bf16_f32 v134, v24, v25
	s_add_u32 s98, s98, 0x4800
	s_addc_u32 s99, s99, 0
	v_mov_b32_dpp v135, v133 quad_perm:[1,0,3,2] row_mask:0xf bank_mask:0xf
	v_mov_b32_dpp v136, v134 quad_perm:[1,0,3,2] row_mask:0xf bank_mask:0xf
	v_perm_b32 v137, v135, v133, v131
	v_perm_b32 v138, v136, v134, v131
	global_store_dword v130, v137, s[98:99]
	global_store_dword v130, v138, s[98:99] offset:256
	v_cvt_pk_bf16_f32 v139, v58, v59
	v_cvt_pk_bf16_f32 v140, v26, v27
	s_add_u32 s98, s98, 0x1800
	s_addc_u32 s99, s99, 0
	v_mov_b32_dpp v141, v139 quad_perm:[1,0,3,2] row_mask:0xf bank_mask:0xf
	v_mov_b32_dpp v142, v140 quad_perm:[1,0,3,2] row_mask:0xf bank_mask:0xf
	v_perm_b32 v143, v141, v139, v131
	v_perm_b32 v144, v142, v140, v131
	global_store_dword v130, v143, s[98:99]
	global_store_dword v130, v144, s[98:99] offset:256
	v_cvt_pk_bf16_f32 v133, v60, v61
	v_cvt_pk_bf16_f32 v134, v28, v29
; __device__ __forceinline__ bf16_t f2bf(float x) { return (bf16_t)(cvtpk(x, 0.f) & 0xffffu); }
; __device__ __forceinline__ int crow(int r, int hi) { return (r & 3) + 8 * (r >> 2) + 4 * hi; }
; template <class Epi>
; __device__ __forceinline__ void gemm8p(const bf16_t* __restrict__ A, int lda, const bf16_t* __restrict__ Bt, int ldb, int K,
;                                        LP lds, const Epi& epi, bool pre = false, const bf16_t* An = nullptr, const bf16_t* Bn = nullptr) {
;     ...
;   int e_rr = wr * 64, e_cc = wc * 32 + r32, e_hi = hi;
;   asm volatile("" : "+v"(e_rr), "+v"(e_cc), "+v"(e_hi));
; #pragma unroll
;   for (int a = 0; a < 2; ++a)
; #pragma unroll
;     for (int b = 0; b < 2; ++b)
; #pragma unroll
;       for (int m = 0; m < 2; ++m) { __builtin_amdgcn_sched_barrier(0); epi(a * 128 + e_rr + m * 32, b * 128 + e_cc, e_hi, acc[a][b][m]); }
; __device__ __forceinline__ void phase_gemm_in1(const Params& p, LP lds) {
;     ...
;     gemm8p(H + (size_t)row0 * 1024, 1024, WT + (size_t)col0 * 1024, 1024, 1024, lds, [&](int rr, int cc, int hi, f32x16 v) __attribute__((always_inline)) {
;       const int col = col0 + cc;
; #pragma unroll
;       for (int r = 0; r < 16; ++r) { const size_t row = row0 + rr + crow(r, hi); Q[row * 1536 + col] = f2bf(v[r]); }
;     }, pre, hasn ? H + (size_t)rown * 1024 : nullptr, hasn ? WT + (size_t)coln * 1024 : nullptr);
	s_add_u32 s98, s98, 0x4800
	s_addc_u32 s99, s99, 0
	v_mov_b32_dpp v135, v133 quad_perm:[1,0,3,2] row_mask:0xf bank_mask:0xf
	v_mov_b32_dpp v136, v134 quad_perm:[1,0,3,2] row_mask:0xf bank_mask:0xf
	v_perm_b32 v137, v135, v133, v131
	v_perm_b32 v138, v136, v134, v131
	global_store_dword v130, v137, s[98:99]
	global_store_dword v130, v138, s[98:99] offset:256
	v_cvt_pk_bf16_f32 v139, v62, v63
	v_cvt_pk_bf16_f32 v140, v30, v31
	s_add_u32 s98, s98, 0x1800
	s_addc_u32 s99, s99, 0
	v_mov_b32_dpp v141, v139 quad_perm:[1,0,3,2] row_mask:0xf bank_mask:0xf
	v_mov_b32_dpp v142, v140 quad_perm:[1,0,3,2] row_mask:0xf bank_mask:0xf
	v_perm_b32 v143, v141, v139, v131
	v_perm_b32 v144, v142, v140, v131
	global_store_dword v130, v143, s[98:99]
	global_store_dword v130, v144, s[98:99] offset:256
	v_cvt_pk_bf16_f32 v133, v32, v33
	v_cvt_pk_bf16_f32 v134, v0, v1
	s_add_u32 s98, s98, 0x4800
	s_addc_u32 s99, s99, 0
	v_mov_b32_dpp v135, v133 quad_perm:[1,0,3,2] row_mask:0xf bank_mask:0xf
	v_mov_b32_dpp v136, v134 quad_perm:[1,0,3,2] row_mask:0xf bank_mask:0xf
	v_perm_b32 v137, v135, v133, v131
	v_perm_b32 v138, v136, v134, v131
	global_store_dword v130, v137, s[98:99]
	global_store_dword v130, v138, s[98:99] offset:256
	v_cvt_pk_bf16_f32 v139, v34, v35
	v_cvt_pk_bf16_f32 v140, v2, v3
	s_add_u32 s98, s98, 0x1800
	s_addc_u32 s99, s99, 0
	v_mov_b32_dpp v141, v139 quad_perm:[1,0,3,2] row_mask:0xf bank_mask:0xf
	v_mov_b32_dpp v142, v140 quad_perm:[1,0,3,2] row_mask:0xf bank_mask:0xf
	v_perm_b32 v143, v141, v139, v131
	v_perm_b32 v144, v142, v140, v131
	global_store_dword v130, v143, s[98:99]
	global_store_dword v130, v144, s[98:99] offset:256
	v_cvt_pk_bf16_f32 v133, v36, v37
	v_cvt_pk_bf16_f32 v134, v4, v5
	s_add_u32 s98, s98, 0x4800
	s_addc_u32 s99, s99, 0
	v_mov_b32_dpp v135, v133 quad_perm:[1,0,3,2] row_mask:0xf bank_mask:0xf
	v_mov_b32_dpp v136, v134 quad_perm:[1,0,3,2] row_mask:0xf bank_mask:0xf
	v_perm_b32 v137, v135, v133, v131
	v_perm_b32 v138, v136, v134, v131
	global_store_dword v130, v137, s[98:99]
	global_store_dword v130, v138, s[98:99] offset:256
	v_cvt_pk_bf16_f32 v139, v38, v39
	v_cvt_pk_bf16_f32 v140, v6, v7
	s_add_u32 s98, s98, 0x1800
	s_addc_u32 s99, s99, 0
	v_mov_b32_dpp v141, v139 quad_perm:[1,0,3,2] row_mask:0xf bank_mask:0xf
	v_mov_b32_dpp v142, v140 quad_perm:[1,0,3,2] row_mask:0xf bank_mask:0xf
	v_perm_b32 v143, v141, v139, v131
	v_perm_b32 v144, v142, v140, v131
	global_store_dword v130, v143, s[98:99]
	global_store_dword v130, v144, s[98:99] offset:256
	v_cvt_pk_bf16_f32 v133, v40, v41
	v_cvt_pk_bf16_f32 v134, v8, v9
	s_add_u32 s98, s98, 0x4800
	s_addc_u32 s99, s99, 0
	v_mov_b32_dpp v135, v133 quad_perm:[1,0,3,2] row_mask:0xf bank_mask:0xf
	v_mov_b32_dpp v136, v134 quad_perm:[1,0,3,2] row_mask:0xf bank_mask:0xf
	v_perm_b32 v137, v135, v133, v131
	v_perm_b32 v138, v136, v134, v131
	global_store_dword v130, v137, s[98:99]
	global_store_dword v130, v138, s[98:99] offset:256
	v_cvt_pk_bf16_f32 v139, v42, v43
	v_cvt_pk_bf16_f32 v140, v10, v11
	s_add_u32 s98, s98, 0x1800
	s_addc_u32 s99, s99, 0
	v_mov_b32_dpp v141, v139 quad_perm:[1,0,3,2] row_mask:0xf bank_mask:0xf
	v_mov_b32_dpp v142, v140 quad_perm:[1,0,3,2] row_mask:0xf bank_mask:0xf
	v_perm_b32 v143, v141, v139, v131
	v_perm_b32 v144, v142, v140, v131
	global_store_dword v130, v143, s[98:99]
	global_store_dword v130, v144, s[98:99] offset:256
	v_cvt_pk_bf16_f32 v133, v44, v45
	v_cvt_pk_bf16_f32 v134, v12, v13
	s_add_u32 s98, s98, 0x4800
	s_addc_u32 s99, s99, 0
	v_mov_b32_dpp v135, v133 quad_perm:[1,0,3,2] row_mask:0xf bank_mask:0xf
	v_mov_b32_dpp v136, v134 quad_perm:[1,0,3,2] row_mask:0xf bank_mask:0xf
	v_perm_b32 v137, v135, v133, v131
	v_perm_b32 v138, v136, v134, v131
	global_store_dword v130, v137, s[98:99]
	global_store_dword v130, v138, s[98:99] offset:256
	v_cvt_pk_bf16_f32 v139, v46, v47
	v_cvt_pk_bf16_f32 v140, v14, v15
	s_add_u32 s98, s98, 0x1800
	s_addc_u32 s99, s99, 0
	v_mov_b32_dpp v141, v139 quad_perm:[1,0,3,2] row_mask:0xf bank_mask:0xf
	v_mov_b32_dpp v142, v140 quad_perm:[1,0,3,2] row_mask:0xf bank_mask:0xf
	v_perm_b32 v143, v141, v139, v131
	v_perm_b32 v144, v142, v140, v131
	global_store_dword v130, v143, s[98:99]
	global_store_dword v130, v144, s[98:99] offset:256
	s_andn2_b64 vcc, exec, s[68:69]
	s_mov_b64 s[72:73], -1
	s_cbranch_vccz .LBB0_1958

; __device__ __forceinline__ bf16_t f2bf(float x) { return (bf16_t)(cvtpk(x, 0.f) & 0xffffu); }
; __device__ __forceinline__ int crow(int r, int hi) { return (r & 3) + 8 * (r >> 2) + 4 * hi; }
; template <class Epi>
; __device__ __forceinline__ void gemm8p(const bf16_t* __restrict__ A, int lda, const bf16_t* __restrict__ Bt, int ldb, int K,
;                                        LP lds, const Epi& epi, bool pre = false, const bf16_t* An = nullptr, const bf16_t* Bn = nullptr) {
;     ...
;   int e_rr = wr * 64, e_cc = wc * 32 + r32, e_hi = hi;
;   asm volatile("" : "+v"(e_rr), "+v"(e_cc), "+v"(e_hi));
; #pragma unroll
;   for (int a = 0; a < 2; ++a)
; #pragma unroll
;     for (int b = 0; b < 2; ++b)
; #pragma unroll
;       for (int m = 0; m < 2; ++m) { __builtin_amdgcn_sched_barrier(0); epi(a * 128 + e_rr + m * 32, b * 128 + e_cc, e_hi, acc[a][b][m]); }
; __device__ __forceinline__ void phase_gemm_w1(const Params& p, const bf16_t* __restrict__ WT, bool xonly, LP lds) {
;     ...
;     gemm8p(H + (size_t)row0 * 1024, 1024, WT + (size_t)col0 * 1024, 1024, 1024, lds, [&](int rr, int cc, int hi, f32x16 v) __attribute__((always_inline)) {
;       const int col = col0 + cc;
; #pragma unroll
;       for (int r = 0; r < 16; ++r) { const size_t row = row0 + rr + crow(r, hi); const float a = fmaxf(v[r], 0.f); __builtin_nontemporal_store(f2bf(a * a), U + row * 4096 + col); }
;     }, pre, hasn ? H + (size_t)rown * 1024 : nullptr, hasn ? WT + (size_t)coln * 1024 : nullptr);
.LBB0_2319:
	s_nop 0
	s_lshl_b32 s100, s66, 13
	s_lshl_b32 s101, s2, 9
	s_add_u32 s100, s100, s101
	s_add_u32 s98, s4, s100
	s_addc_u32 s99, s5, 0
	v_lshl_add_u32 v130, v150, 2, v149
	v_and_b32_e32 v131, 1, v151
	v_add_u32_e32 v130, v130, v131
	v_sub_u32_e32 v132, v151, v131
	v_mul_u32_u24_e32 v130, 0x2000, v130
	v_lshl_add_u32 v130, v132, 1, v130
	v_sub_u32_e32 v132, 0, v131
	v_and_b32_e32 v132, 0x6060606, v132
	v_xor_b32_e32 v131, 0x5040100, v132
	v_max_f32_e32 v112, 0, v112
	v_max_f32_e32 v113, 0, v113
	v_max_f32_e32 v80, 0, v80
	v_max_f32_e32 v81, 0, v81
	v_pk_mul_f32 v[112:113], v[112:113], v[112:113]
	v_pk_mul_f32 v[80:81], v[80:81], v[80:81]
	v_cvt_pk_bf16_f32 v133, v112, v113
	v_cvt_pk_bf16_f32 v134, v80, v81
	s_nop 1
	v_mov_b32_dpp v135, v133 quad_perm:[1,0,3,2] row_mask:0xf bank_mask:0xf
	v_mov_b32_dpp v136, v134 quad_perm:[1,0,3,2] row_mask:0xf bank_mask:0xf
	v_perm_b32 v137, v135, v133, v131
	v_perm_b32 v138, v136, v134, v131
	global_store_dword v130, v137, s[98:99] nt
	global_store_dword v130, v138, s[98:99] offset:256 nt
	v_max_f32_e32 v114, 0, v114
	v_max_f32_e32 v115, 0, v115
	v_max_f32_e32 v82, 0, v82
	v_max_f32_e32 v83, 0, v83
	v_pk_mul_f32 v[114:115], v[114:115], v[114:115]
	v_pk_mul_f32 v[82:83], v[82:83], v[82:83]
	v_cvt_pk_bf16_f32 v139, v114, v115
	v_cvt_pk_bf16_f32 v140, v82, v83
	s_add_u32 s98, s98, 0x4000
	s_addc_u32 s99, s99, 0
	v_mov_b32_dpp v141, v139 quad_perm:[1,0,3,2] row_mask:0xf bank_mask:0xf
	v_mov_b32_dpp v142, v140 quad_perm:[1,0,3,2] row_mask:0xf bank_mask:0xf
	v_perm_b32 v143, v141, v139, v131
	v_perm_b32 v144, v142, v140, v131
	global_store_dword v130, v143, s[98:99] nt
	global_store_dword v130, v144, s[98:99] offset:256 nt
	v_max_f32_e32 v116, 0, v116
	v_max_f32_e32 v117, 0, v117
	v_max_f32_e32 v84, 0, v84
	v_max_f32_e32 v85, 0, v85
	v_pk_mul_f32 v[116:117], v[116:117], v[116:117]
	v_pk_mul_f32 v[84:85], v[84:85], v[84:85]
	v_cvt_pk_bf16_f32 v133, v116, v117
	v_cvt_pk_bf16_f32 v134, v84, v85
	s_add_u32 s98, s98, 0xc000
	s_addc_u32 s99, s99, 0
	v_mov_b32_dpp v135, v133 quad_perm:[1,0,3,2] row_mask:0xf bank_mask:0xf
	v_mov_b32_dpp v136, v134 quad_perm:[1,0,3,2] row_mask:0xf bank_mask:0xf
	v_perm_b32 v137, v135, v133, v131
	v_perm_b32 v138, v136, v134, v131
	global_store_dword v130, v137, s[98:99] nt
	global_store_dword v130, v138, s[98:99] offset:256 nt
	v_max_f32_e32 v118, 0, v118
	v_max_f32_e32 v119, 0, v119
	v_max_f32_e32 v86, 0, v86
	v_max_f32_e32 v87, 0, v87
	v_pk_mul_f32 v[118:119], v[118:119], v[118:119]
	v_pk_mul_f32 v[86:87], v[86:87], v[86:87]
	v_cvt_pk_bf16_f32 v139, v118, v119
	v_cvt_pk_bf16_f32 v140, v86, v87
	s_add_u32 s98, s98, 0x4000
	s_addc_u32 s99, s99, 0
	v_mov_b32_dpp v141, v139 quad_perm:[1,0,3,2] row_mask:0xf bank_mask:0xf
	v_mov_b32_dpp v142, v140 quad_perm:[1,0,3,2] row_mask:0xf bank_mask:0xf
	v_perm_b32 v143, v141, v139, v131
	v_perm_b32 v144, v142, v140, v131
	global_store_dword v130, v143, s[98:99] nt
	global_store_dword v130, v144, s[98:99] offset:256 nt
	v_max_f32_e32 v120, 0, v120
	v_max_f32_e32 v121, 0, v121
	v_max_f32_e32 v88, 0, v88
	v_max_f32_e32 v89, 0, v89
	v_pk_mul_f32 v[120:121], v[120:121], v[120:121]
	v_pk_mul_f32 v[88:89], v[88:89], v[88:89]
	v_cvt_pk_bf16_f32 v133, v120, v121
	v_cvt_pk_bf16_f32 v134, v88, v89
	s_add_u32 s98, s98, 0xc000
	s_addc_u32 s99, s99, 0
	v_mov_b32_dpp v135, v133 quad_perm:[1,0,3,2] row_mask:0xf bank_mask:0xf
	v_mov_b32_dpp v136, v134 quad_perm:[1,0,3,2] row_mask:0xf bank_mask:0xf
	v_perm_b32 v137, v135, v133, v131
	v_perm_b32 v138, v136, v134, v131
	global_store_dword v130, v137, s[98:99] nt
	global_store_dword v130, v138, s[98:99] offset:256 nt
	v_max_f32_e32 v122, 0, v122
	v_max_f32_e32 v123, 0, v123
	v_max_f32_e32 v90, 0, v90
	v_max_f32_e32 v91, 0, v91
	v_pk_mul_f32 v[122:123], v[122:123], v[122:123]
	v_pk_mul_f32 v[90:91], v[90:91], v[90:91]
	v_cvt_pk_bf16_f32 v139, v122, v123
	v_cvt_pk_bf16_f32 v140, v90, v91
	s_add_u32 s98, s98, 0x4000
	s_addc_u32 s99, s99, 0
	v_mov_b32_dpp v141, v139 quad_perm:[1,0,3,2] row_mask:0xf bank_mask:0xf
	v_mov_b32_dpp v142, v140 quad_perm:[1,0,3,2] row_mask:0xf bank_mask:0xf
	v_perm_b32 v143, v141, v139, v131
	v_perm_b32 v144, v142, v140, v131
	global_store_dword v130, v143, s[98:99] nt
	global_store_dword v130, v144, s[98:99] offset:256 nt
	v_max_f32_e32 v124, 0, v124
	v_max_f32_e32 v125, 0, v125
	v_max_f32_e32 v92, 0, v92
	v_max_f32_e32 v93, 0, v93
	v_pk_mul_f32 v[124:125], v[124:125], v[124:125]
	v_pk_mul_f32 v[92:93], v[92:93], v[92:93]
	v_cvt_pk_bf16_f32 v133, v124, v125
	v_cvt_pk_bf16_f32 v134, v92, v93
	s_add_u32 s98, s98, 0xc000
	s_addc_u32 s99, s99, 0
	v_mov_b32_dpp v135, v133 quad_perm:[1,0,3,2] row_mask:0xf bank_mask:0xf
	v_mov_b32_dpp v136, v134 quad_perm:[1,0,3,2] row_mask:0xf bank_mask:0xf
	v_perm_b32 v137, v135, v133, v131
	v_perm_b32 v138, v136, v134, v131
	global_store_dword v130, v137, s[98:99] nt
	global_store_dword v130, v138, s[98:99] offset:256 nt
	v_max_f32_e32 v126, 0, v126
	v_max_f32_e32 v127, 0, v127
	v_max_f32_e32 v94, 0, v94
	v_max_f32_e32 v95, 0, v95
	v_pk_mul_f32 v[126:127], v[126:127], v[126:127]
	v_pk_mul_f32 v[94:95], v[94:95], v[94:95]
	v_cvt_pk_bf16_f32 v139, v126, v127
	v_cvt_pk_bf16_f32 v140, v94, v95
	s_add_u32 s98, s98, 0x4000
	s_addc_u32 s99, s99, 0
	v_mov_b32_dpp v141, v139 quad_perm:[1,0,3,2] row_mask:0xf bank_mask:0xf
	v_mov_b32_dpp v142, v140 quad_perm:[1,0,3,2] row_mask:0xf bank_mask:0xf
	v_perm_b32 v143, v141, v139, v131
	v_perm_b32 v144, v142, v140, v131
	global_store_dword v130, v143, s[98:99] nt
	global_store_dword v130, v144, s[98:99] offset:256 nt
	v_max_f32_e32 v96, 0, v96
	v_max_f32_e32 v97, 0, v97
	v_max_f32_e32 v64, 0, v64
	v_max_f32_e32 v65, 0, v65
; __device__ __forceinline__ bf16_t f2bf(float x) { return (bf16_t)(cvtpk(x, 0.f) & 0xffffu); }
; __device__ __forceinline__ int crow(int r, int hi) { return (r & 3) + 8 * (r >> 2) + 4 * hi; }
; template <class Epi>
; __device__ __forceinline__ void gemm8p(const bf16_t* __restrict__ A, int lda, const bf16_t* __restrict__ Bt, int ldb, int K,
;                                        LP lds, const Epi& epi, bool pre = false, const bf16_t* An = nullptr, const bf16_t* Bn = nullptr) {
;     ...
;   int e_rr = wr * 64, e_cc = wc * 32 + r32, e_hi = hi;
;   asm volatile("" : "+v"(e_rr), "+v"(e_cc), "+v"(e_hi));
; #pragma unroll
;   for (int a = 0; a < 2; ++a)
; #pragma unroll
;     for (int b = 0; b < 2; ++b)
; #pragma unroll
;       for (int m = 0; m < 2; ++m) { __builtin_amdgcn_sched_barrier(0); epi(a * 128 + e_rr + m * 32, b * 128 + e_cc, e_hi, acc[a][b][m]); }
; __device__ __forceinline__ void phase_gemm_w1(const Params& p, const bf16_t* __restrict__ WT, bool xonly, LP lds) {
;     ...
;     gemm8p(H + (size_t)row0 * 1024, 1024, WT + (size_t)col0 * 1024, 1024, 1024, lds, [&](int rr, int cc, int hi, f32x16 v) __attribute__((always_inline)) {
;       const int col = col0 + cc;
; #pragma unroll
;       for (int r = 0; r < 16; ++r) { const size_t row = row0 + rr + crow(r, hi); const float a = fmaxf(v[r], 0.f); __builtin_nontemporal_store(f2bf(a * a), U + row * 4096 + col); }
;     }, pre, hasn ? H + (size_t)rown * 1024 : nullptr, hasn ? WT + (size_t)coln * 1024 : nullptr);
	v_pk_mul_f32 v[96:97], v[96:97], v[96:97]
	v_pk_mul_f32 v[64:65], v[64:65], v[64:65]
	v_cvt_pk_bf16_f32 v133, v96, v97
	v_cvt_pk_bf16_f32 v134, v64, v65
	s_add_u32 s98, s98, 0xc000
	s_addc_u32 s99, s99, 0
	v_mov_b32_dpp v135, v133 quad_perm:[1,0,3,2] row_mask:0xf bank_mask:0xf
	v_mov_b32_dpp v136, v134 quad_perm:[1,0,3,2] row_mask:0xf bank_mask:0xf
	v_perm_b32 v137, v135, v133, v131
	v_perm_b32 v138, v136, v134, v131
	global_store_dword v130, v137, s[98:99] nt
	global_store_dword v130, v138, s[98:99] offset:256 nt
	v_max_f32_e32 v98, 0, v98
	v_max_f32_e32 v99, 0, v99
	v_max_f32_e32 v66, 0, v66
	v_max_f32_e32 v67, 0, v67
	v_pk_mul_f32 v[98:99], v[98:99], v[98:99]
	v_pk_mul_f32 v[66:67], v[66:67], v[66:67]
	v_cvt_pk_bf16_f32 v139, v98, v99
	v_cvt_pk_bf16_f32 v140, v66, v67
	s_add_u32 s98, s98, 0x4000
	s_addc_u32 s99, s99, 0
	v_mov_b32_dpp v141, v139 quad_perm:[1,0,3,2] row_mask:0xf bank_mask:0xf
	v_mov_b32_dpp v142, v140 quad_perm:[1,0,3,2] row_mask:0xf bank_mask:0xf
	v_perm_b32 v143, v141, v139, v131
	v_perm_b32 v144, v142, v140, v131
	global_store_dword v130, v143, s[98:99] nt
	global_store_dword v130, v144, s[98:99] offset:256 nt
	v_max_f32_e32 v100, 0, v100
	v_max_f32_e32 v101, 0, v101
	v_max_f32_e32 v68, 0, v68
	v_max_f32_e32 v69, 0, v69
	v_pk_mul_f32 v[100:101], v[100:101], v[100:101]
	v_pk_mul_f32 v[68:69], v[68:69], v[68:69]
	v_cvt_pk_bf16_f32 v133, v100, v101
	v_cvt_pk_bf16_f32 v134, v68, v69
	s_add_u32 s98, s98, 0xc000
	s_addc_u32 s99, s99, 0
	v_mov_b32_dpp v135, v133 quad_perm:[1,0,3,2] row_mask:0xf bank_mask:0xf
	v_mov_b32_dpp v136, v134 quad_perm:[1,0,3,2] row_mask:0xf bank_mask:0xf
	v_perm_b32 v137, v135, v133, v131
	v_perm_b32 v138, v136, v134, v131
	global_store_dword v130, v137, s[98:99] nt
	global_store_dword v130, v138, s[98:99] offset:256 nt
	v_max_f32_e32 v102, 0, v102
	v_max_f32_e32 v103, 0, v103
	v_max_f32_e32 v70, 0, v70
	v_max_f32_e32 v71, 0, v71
	v_pk_mul_f32 v[102:103], v[102:103], v[102:103]
	v_pk_mul_f32 v[70:71], v[70:71], v[70:71]
	v_cvt_pk_bf16_f32 v139, v102, v103
	v_cvt_pk_bf16_f32 v140, v70, v71
	s_add_u32 s98, s98, 0x4000
	s_addc_u32 s99, s99, 0
	v_mov_b32_dpp v141, v139 quad_perm:[1,0,3,2] row_mask:0xf bank_mask:0xf
	v_mov_b32_dpp v142, v140 quad_perm:[1,0,3,2] row_mask:0xf bank_mask:0xf
	v_perm_b32 v143, v141, v139, v131
	v_perm_b32 v144, v142, v140, v131
	global_store_dword v130, v143, s[98:99] nt
	global_store_dword v130, v144, s[98:99] offset:256 nt
	v_max_f32_e32 v104, 0, v104
	v_max_f32_e32 v105, 0, v105
	v_max_f32_e32 v72, 0, v72
	v_max_f32_e32 v73, 0, v73
	v_pk_mul_f32 v[104:105], v[104:105], v[104:105]
	v_pk_mul_f32 v[72:73], v[72:73], v[72:73]
	v_cvt_pk_bf16_f32 v133, v104, v105
	v_cvt_pk_bf16_f32 v134, v72, v73
	s_add_u32 s98, s98, 0xc000
	s_addc_u32 s99, s99, 0
	v_mov_b32_dpp v135, v133 quad_perm:[1,0,3,2] row_mask:0xf bank_mask:0xf
	v_mov_b32_dpp v136, v134 quad_perm:[1,0,3,2] row_mask:0xf bank_mask:0xf
	v_perm_b32 v137, v135, v133, v131
	v_perm_b32 v138, v136, v134, v131
	global_store_dword v130, v137, s[98:99] nt
	global_store_dword v130, v138, s[98:99] offset:256 nt
	v_max_f32_e32 v106, 0, v106
	v_max_f32_e32 v107, 0, v107
	v_max_f32_e32 v74, 0, v74
	v_max_f32_e32 v75, 0, v75
	v_pk_mul_f32 v[106:107], v[106:107], v[106:107]
	v_pk_mul_f32 v[74:75], v[74:75], v[74:75]
	v_cvt_pk_bf16_f32 v139, v106, v107
	v_cvt_pk_bf16_f32 v140, v74, v75
	s_add_u32 s98, s98, 0x4000
	s_addc_u32 s99, s99, 0
	v_mov_b32_dpp v141, v139 quad_perm:[1,0,3,2] row_mask:0xf bank_mask:0xf
	v_mov_b32_dpp v142, v140 quad_perm:[1,0,3,2] row_mask:0xf bank_mask:0xf
	v_perm_b32 v143, v141, v139, v131
	v_perm_b32 v144, v142, v140, v131
	global_store_dword v130, v143, s[98:99] nt
	global_store_dword v130, v144, s[98:99] offset:256 nt
	v_max_f32_e32 v108, 0, v108
	v_max_f32_e32 v109, 0, v109
	v_max_f32_e32 v76, 0, v76
	v_max_f32_e32 v77, 0, v77
	v_pk_mul_f32 v[108:109], v[108:109], v[108:109]
	v_pk_mul_f32 v[76:77], v[76:77], v[76:77]
	v_cvt_pk_bf16_f32 v133, v108, v109
	v_cvt_pk_bf16_f32 v134, v76, v77
	s_add_u32 s98, s98, 0xc000
	s_addc_u32 s99, s99, 0
	v_mov_b32_dpp v135, v133 quad_perm:[1,0,3,2] row_mask:0xf bank_mask:0xf
	v_mov_b32_dpp v136, v134 quad_perm:[1,0,3,2] row_mask:0xf bank_mask:0xf
	v_perm_b32 v137, v135, v133, v131
	v_perm_b32 v138, v136, v134, v131
	global_store_dword v130, v137, s[98:99] nt
	global_store_dword v130, v138, s[98:99] offset:256 nt
	v_max_f32_e32 v110, 0, v110
	v_max_f32_e32 v111, 0, v111
	v_max_f32_e32 v78, 0, v78
	v_max_f32_e32 v79, 0, v79
	v_pk_mul_f32 v[110:111], v[110:111], v[110:111]
	v_pk_mul_f32 v[78:79], v[78:79], v[78:79]
	v_cvt_pk_bf16_f32 v139, v110, v111
	v_cvt_pk_bf16_f32 v140, v78, v79
	s_add_u32 s98, s98, 0x4000
	s_addc_u32 s99, s99, 0
	v_mov_b32_dpp v141, v139 quad_perm:[1,0,3,2] row_mask:0xf bank_mask:0xf
	v_mov_b32_dpp v142, v140 quad_perm:[1,0,3,2] row_mask:0xf bank_mask:0xf
	v_perm_b32 v143, v141, v139, v131
	v_perm_b32 v144, v142, v140, v131
	global_store_dword v130, v143, s[98:99] nt
	global_store_dword v130, v144, s[98:99] offset:256 nt
	v_max_f32_e32 v48, 0, v48
	v_max_f32_e32 v49, 0, v49
	v_max_f32_e32 v16, 0, v16
	v_max_f32_e32 v17, 0, v17
	v_pk_mul_f32 v[48:49], v[48:49], v[48:49]
	v_pk_mul_f32 v[16:17], v[16:17], v[16:17]
	v_cvt_pk_bf16_f32 v133, v48, v49
	v_cvt_pk_bf16_f32 v134, v16, v17
	s_add_u32 s98, s98, 0x8c000
	s_addc_u32 s99, s99, 0
	v_mov_b32_dpp v135, v133 quad_perm:[1,0,3,2] row_mask:0xf bank_mask:0xf
	v_mov_b32_dpp v136, v134 quad_perm:[1,0,3,2] row_mask:0xf bank_mask:0xf
	v_perm_b32 v137, v135, v133, v131
	v_perm_b32 v138, v136, v134, v131
	global_store_dword v130, v137, s[98:99] nt
	global_store_dword v130, v138, s[98:99] offset:256 nt
	v_max_f32_e32 v50, 0, v50
; __device__ __forceinline__ bf16_t f2bf(float x) { return (bf16_t)(cvtpk(x, 0.f) & 0xffffu); }
; __device__ __forceinline__ int crow(int r, int hi) { return (r & 3) + 8 * (r >> 2) + 4 * hi; }
; template <class Epi>
; __device__ __forceinline__ void gemm8p(const bf16_t* __restrict__ A, int lda, const bf16_t* __restrict__ Bt, int ldb, int K,
;                                        LP lds, const Epi& epi, bool pre = false, const bf16_t* An = nullptr, const bf16_t* Bn = nullptr) {
;     ...
;   int e_rr = wr * 64, e_cc = wc * 32 + r32, e_hi = hi;
;   asm volatile("" : "+v"(e_rr), "+v"(e_cc), "+v"(e_hi));
; #pragma unroll
;   for (int a = 0; a < 2; ++a)
; #pragma unroll
;     for (int b = 0; b < 2; ++b)
; #pragma unroll
;       for (int m = 0; m < 2; ++m) { __builtin_amdgcn_sched_barrier(0); epi(a * 128 + e_rr + m * 32, b * 128 + e_cc, e_hi, acc[a][b][m]); }
; __device__ __forceinline__ void phase_gemm_w1(const Params& p, const bf16_t* __restrict__ WT, bool xonly, LP lds) {
;     ...
;     gemm8p(H + (size_t)row0 * 1024, 1024, WT + (size_t)col0 * 1024, 1024, 1024, lds, [&](int rr, int cc, int hi, f32x16 v) __attribute__((always_inline)) {
;       const int col = col0 + cc;
; #pragma unroll
;       for (int r = 0; r < 16; ++r) { const size_t row = row0 + rr + crow(r, hi); const float a = fmaxf(v[r], 0.f); __builtin_nontemporal_store(f2bf(a * a), U + row * 4096 + col); }
;     }, pre, hasn ? H + (size_t)rown * 1024 : nullptr, hasn ? WT + (size_t)coln * 1024 : nullptr);
	v_max_f32_e32 v51, 0, v51
	v_max_f32_e32 v18, 0, v18
	v_max_f32_e32 v19, 0, v19
	v_pk_mul_f32 v[50:51], v[50:51], v[50:51]
	v_pk_mul_f32 v[18:19], v[18:19], v[18:19]
	v_cvt_pk_bf16_f32 v139, v50, v51
	v_cvt_pk_bf16_f32 v140, v18, v19
	s_add_u32 s98, s98, 0x4000
	s_addc_u32 s99, s99, 0
	v_mov_b32_dpp v141, v139 quad_perm:[1,0,3,2] row_mask:0xf bank_mask:0xf
	v_mov_b32_dpp v142, v140 quad_perm:[1,0,3,2] row_mask:0xf bank_mask:0xf
	v_perm_b32 v143, v141, v139, v131
	v_perm_b32 v144, v142, v140, v131
	global_store_dword v130, v143, s[98:99] nt
	global_store_dword v130, v144, s[98:99] offset:256 nt
	v_max_f32_e32 v52, 0, v52
	v_max_f32_e32 v53, 0, v53
	v_max_f32_e32 v20, 0, v20
	v_max_f32_e32 v21, 0, v21
	v_pk_mul_f32 v[52:53], v[52:53], v[52:53]
	v_pk_mul_f32 v[20:21], v[20:21], v[20:21]
	v_cvt_pk_bf16_f32 v133, v52, v53
	v_cvt_pk_bf16_f32 v134, v20, v21
	s_add_u32 s98, s98, 0xc000
	s_addc_u32 s99, s99, 0
	v_mov_b32_dpp v135, v133 quad_perm:[1,0,3,2] row_mask:0xf bank_mask:0xf
	v_mov_b32_dpp v136, v134 quad_perm:[1,0,3,2] row_mask:0xf bank_mask:0xf
	v_perm_b32 v137, v135, v133, v131
	v_perm_b32 v138, v136, v134, v131
	global_store_dword v130, v137, s[98:99] nt
	global_store_dword v130, v138, s[98:99] offset:256 nt
	v_max_f32_e32 v54, 0, v54
	v_max_f32_e32 v55, 0, v55
	v_max_f32_e32 v22, 0, v22
	v_max_f32_e32 v23, 0, v23
	v_pk_mul_f32 v[54:55], v[54:55], v[54:55]
	v_pk_mul_f32 v[22:23], v[22:23], v[22:23]
	v_cvt_pk_bf16_f32 v139, v54, v55
	v_cvt_pk_bf16_f32 v140, v22, v23
	s_add_u32 s98, s98, 0x4000
	s_addc_u32 s99, s99, 0
	v_mov_b32_dpp v141, v139 quad_perm:[1,0,3,2] row_mask:0xf bank_mask:0xf
	v_mov_b32_dpp v142, v140 quad_perm:[1,0,3,2] row_mask:0xf bank_mask:0xf
	v_perm_b32 v143, v141, v139, v131
	v_perm_b32 v144, v142, v140, v131
	global_store_dword v130, v143, s[98:99] nt
	global_store_dword v130, v144, s[98:99] offset:256 nt
	v_max_f32_e32 v56, 0, v56
	v_max_f32_e32 v57, 0, v57
	v_max_f32_e32 v24, 0, v24
	v_max_f32_e32 v25, 0, v25
	v_pk_mul_f32 v[56:57], v[56:57], v[56:57]
	v_pk_mul_f32 v[24:25], v[24:25], v[24:25]
	v_cvt_pk_bf16_f32 v133, v56, v57
	v_cvt_pk_bf16_f32 v134, v24, v25
	s_add_u32 s98, s98, 0xc000
	s_addc_u32 s99, s99, 0
	v_mov_b32_dpp v135, v133 quad_perm:[1,0,3,2] row_mask:0xf bank_mask:0xf
	v_mov_b32_dpp v136, v134 quad_perm:[1,0,3,2] row_mask:0xf bank_mask:0xf
	v_perm_b32 v137, v135, v133, v131
	v_perm_b32 v138, v136, v134, v131
	global_store_dword v130, v137, s[98:99] nt
	global_store_dword v130, v138, s[98:99] offset:256 nt
	v_max_f32_e32 v58, 0, v58
	v_max_f32_e32 v59, 0, v59
	v_max_f32_e32 v26, 0, v26
	v_max_f32_e32 v27, 0, v27
	v_pk_mul_f32 v[58:59], v[58:59], v[58:59]
	v_pk_mul_f32 v[26:27], v[26:27], v[26:27]
	v_cvt_pk_bf16_f32 v139, v58, v59
	v_cvt_pk_bf16_f32 v140, v26, v27
	s_add_u32 s98, s98, 0x4000
	s_addc_u32 s99, s99, 0
	v_mov_b32_dpp v141, v139 quad_perm:[1,0,3,2] row_mask:0xf bank_mask:0xf
	v_mov_b32_dpp v142, v140 quad_perm:[1,0,3,2] row_mask:0xf bank_mask:0xf
	v_perm_b32 v143, v141, v139, v131
	v_perm_b32 v144, v142, v140, v131
	global_store_dword v130, v143, s[98:99] nt
	global_store_dword v130, v144, s[98:99] offset:256 nt
	v_max_f32_e32 v60, 0, v60
	v_max_f32_e32 v61, 0, v61
	v_max_f32_e32 v28, 0, v28
	v_max_f32_e32 v29, 0, v29
	v_pk_mul_f32 v[60:61], v[60:61], v[60:61]
	v_pk_mul_f32 v[28:29], v[28:29], v[28:29]
	v_cvt_pk_bf16_f32 v133, v60, v61
	v_cvt_pk_bf16_f32 v134, v28, v29
	s_add_u32 s98, s98, 0xc000
	s_addc_u32 s99, s99, 0
	v_mov_b32_dpp v135, v133 quad_perm:[1,0,3,2] row_mask:0xf bank_mask:0xf
	v_mov_b32_dpp v136, v134 quad_perm:[1,0,3,2] row_mask:0xf bank_mask:0xf
	v_perm_b32 v137, v135, v133, v131
	v_perm_b32 v138, v136, v134, v131
	global_store_dword v130, v137, s[98:99] nt
	global_store_dword v130, v138, s[98:99] offset:256 nt
	v_max_f32_e32 v62, 0, v62
	v_max_f32_e32 v63, 0, v63
	v_max_f32_e32 v30, 0, v30
	v_max_f32_e32 v31, 0, v31
	v_pk_mul_f32 v[62:63], v[62:63], v[62:63]
	v_pk_mul_f32 v[30:31], v[30:31], v[30:31]
	v_cvt_pk_bf16_f32 v139, v62, v63
	v_cvt_pk_bf16_f32 v140, v30, v31
	s_add_u32 s98, s98, 0x4000
	s_addc_u32 s99, s99, 0
	v_mov_b32_dpp v141, v139 quad_perm:[1,0,3,2] row_mask:0xf bank_mask:0xf
	v_mov_b32_dpp v142, v140 quad_perm:[1,0,3,2] row_mask:0xf bank_mask:0xf
	v_perm_b32 v143, v141, v139, v131
	v_perm_b32 v144, v142, v140, v131
	global_store_dword v130, v143, s[98:99] nt
	global_store_dword v130, v144, s[98:99] offset:256 nt
	v_max_f32_e32 v32, 0, v32
	v_max_f32_e32 v33, 0, v33
	v_max_f32_e32 v0, 0, v0
	v_max_f32_e32 v1, 0, v1
	v_pk_mul_f32 v[32:33], v[32:33], v[32:33]
	v_pk_mul_f32 v[0:1], v[0:1], v[0:1]
	v_cvt_pk_bf16_f32 v133, v32, v33
	v_cvt_pk_bf16_f32 v134, v0, v1
	s_add_u32 s98, s98, 0xc000
	s_addc_u32 s99, s99, 0
; __device__ __forceinline__ bf16_t f2bf(float x) { return (bf16_t)(cvtpk(x, 0.f) & 0xffffu); }
; __device__ __forceinline__ int crow(int r, int hi) { return (r & 3) + 8 * (r >> 2) + 4 * hi; }
; template <class Epi>
; __device__ __forceinline__ void gemm8p(const bf16_t* __restrict__ A, int lda, const bf16_t* __restrict__ Bt, int ldb, int K,
;                                        LP lds, const Epi& epi, bool pre = false, const bf16_t* An = nullptr, const bf16_t* Bn = nullptr) {
;     ...
;   int e_rr = wr * 64, e_cc = wc * 32 + r32, e_hi = hi;
;   asm volatile("" : "+v"(e_rr), "+v"(e_cc), "+v"(e_hi));
; #pragma unroll
;   for (int a = 0; a < 2; ++a)
; #pragma unroll
;     for (int b = 0; b < 2; ++b)
; #pragma unroll
;       for (int m = 0; m < 2; ++m) { __builtin_amdgcn_sched_barrier(0); epi(a * 128 + e_rr + m * 32, b * 128 + e_cc, e_hi, acc[a][b][m]); }
; __device__ __forceinline__ void phase_gemm_w1(const Params& p, const bf16_t* __restrict__ WT, bool xonly, LP lds) {
;     ...
;     gemm8p(H + (size_t)row0 * 1024, 1024, WT + (size_t)col0 * 1024, 1024, 1024, lds, [&](int rr, int cc, int hi, f32x16 v) __attribute__((always_inline)) {
;       const int col = col0 + cc;
; #pragma unroll
;       for (int r = 0; r < 16; ++r) { const size_t row = row0 + rr + crow(r, hi); const float a = fmaxf(v[r], 0.f); __builtin_nontemporal_store(f2bf(a * a), U + row * 4096 + col); }
;     }, pre, hasn ? H + (size_t)rown * 1024 : nullptr, hasn ? WT + (size_t)coln * 1024 : nullptr);
	v_mov_b32_dpp v135, v133 quad_perm:[1,0,3,2] row_mask:0xf bank_mask:0xf
	v_mov_b32_dpp v136, v134 quad_perm:[1,0,3,2] row_mask:0xf bank_mask:0xf
	v_perm_b32 v137, v135, v133, v131
	v_perm_b32 v138, v136, v134, v131
	global_store_dword v130, v137, s[98:99] nt
	global_store_dword v130, v138, s[98:99] offset:256 nt
	v_max_f32_e32 v34, 0, v34
	v_max_f32_e32 v35, 0, v35
	v_max_f32_e32 v2, 0, v2
	v_max_f32_e32 v3, 0, v3
	v_pk_mul_f32 v[34:35], v[34:35], v[34:35]
	v_pk_mul_f32 v[2:3], v[2:3], v[2:3]
	v_cvt_pk_bf16_f32 v139, v34, v35
	v_cvt_pk_bf16_f32 v140, v2, v3
	s_add_u32 s98, s98, 0x4000
	s_addc_u32 s99, s99, 0
	v_mov_b32_dpp v141, v139 quad_perm:[1,0,3,2] row_mask:0xf bank_mask:0xf
	v_mov_b32_dpp v142, v140 quad_perm:[1,0,3,2] row_mask:0xf bank_mask:0xf
	v_perm_b32 v143, v141, v139, v131
	v_perm_b32 v144, v142, v140, v131
	global_store_dword v130, v143, s[98:99] nt
	global_store_dword v130, v144, s[98:99] offset:256 nt
	v_max_f32_e32 v36, 0, v36
	v_max_f32_e32 v37, 0, v37
	v_max_f32_e32 v4, 0, v4
	v_max_f32_e32 v5, 0, v5
	v_pk_mul_f32 v[36:37], v[36:37], v[36:37]
	v_pk_mul_f32 v[4:5], v[4:5], v[4:5]
	v_cvt_pk_bf16_f32 v133, v36, v37
	v_cvt_pk_bf16_f32 v134, v4, v5
	s_add_u32 s98, s98, 0xc000
	s_addc_u32 s99, s99, 0
	v_mov_b32_dpp v135, v133 quad_perm:[1,0,3,2] row_mask:0xf bank_mask:0xf
	v_mov_b32_dpp v136, v134 quad_perm:[1,0,3,2] row_mask:0xf bank_mask:0xf
	v_perm_b32 v137, v135, v133, v131
	v_perm_b32 v138, v136, v134, v131
	global_store_dword v130, v137, s[98:99] nt
	global_store_dword v130, v138, s[98:99] offset:256 nt
	v_max_f32_e32 v38, 0, v38
	v_max_f32_e32 v39, 0, v39
	v_max_f32_e32 v6, 0, v6
	v_max_f32_e32 v7, 0, v7
	v_pk_mul_f32 v[38:39], v[38:39], v[38:39]
	v_pk_mul_f32 v[6:7], v[6:7], v[6:7]
	v_cvt_pk_bf16_f32 v139, v38, v39
	v_cvt_pk_bf16_f32 v140, v6, v7
	s_add_u32 s98, s98, 0x4000
	s_addc_u32 s99, s99, 0
	v_mov_b32_dpp v141, v139 quad_perm:[1,0,3,2] row_mask:0xf bank_mask:0xf
	v_mov_b32_dpp v142, v140 quad_perm:[1,0,3,2] row_mask:0xf bank_mask:0xf
	v_perm_b32 v143, v141, v139, v131
	v_perm_b32 v144, v142, v140, v131
	global_store_dword v130, v143, s[98:99] nt
	global_store_dword v130, v144, s[98:99] offset:256 nt
	v_max_f32_e32 v40, 0, v40
	v_max_f32_e32 v41, 0, v41
	v_max_f32_e32 v8, 0, v8
	v_max_f32_e32 v9, 0, v9
	v_pk_mul_f32 v[40:41], v[40:41], v[40:41]
	v_pk_mul_f32 v[8:9], v[8:9], v[8:9]
	v_cvt_pk_bf16_f32 v133, v40, v41
	v_cvt_pk_bf16_f32 v134, v8, v9
	s_add_u32 s98, s98, 0xc000
	s_addc_u32 s99, s99, 0
	v_mov_b32_dpp v135, v133 quad_perm:[1,0,3,2] row_mask:0xf bank_mask:0xf
	v_mov_b32_dpp v136, v134 quad_perm:[1,0,3,2] row_mask:0xf bank_mask:0xf
	v_perm_b32 v137, v135, v133, v131
	v_perm_b32 v138, v136, v134, v131
	global_store_dword v130, v137, s[98:99] nt
	global_store_dword v130, v138, s[98:99] offset:256 nt
	v_max_f32_e32 v42, 0, v42
	v_max_f32_e32 v43, 0, v43
	v_max_f32_e32 v10, 0, v10
	v_max_f32_e32 v11, 0, v11
	v_pk_mul_f32 v[42:43], v[42:43], v[42:43]
	v_pk_mul_f32 v[10:11], v[10:11], v[10:11]
	v_cvt_pk_bf16_f32 v139, v42, v43
	v_cvt_pk_bf16_f32 v140, v10, v11
	s_add_u32 s98, s98, 0x4000
	s_addc_u32 s99, s99, 0
	v_mov_b32_dpp v141, v139 quad_perm:[1,0,3,2] row_mask:0xf bank_mask:0xf
	v_mov_b32_dpp v142, v140 quad_perm:[1,0,3,2] row_mask:0xf bank_mask:0xf
	v_perm_b32 v143, v141, v139, v131
	v_perm_b32 v144, v142, v140, v131
	global_store_dword v130, v143, s[98:99] nt
	global_store_dword v130, v144, s[98:99] offset:256 nt
	v_max_f32_e32 v44, 0, v44
	v_max_f32_e32 v45, 0, v45
	v_max_f32_e32 v12, 0, v12
	v_max_f32_e32 v13, 0, v13
	v_pk_mul_f32 v[44:45], v[44:45], v[44:45]
	v_pk_mul_f32 v[12:13], v[12:13], v[12:13]
	v_cvt_pk_bf16_f32 v133, v44, v45
	v_cvt_pk_bf16_f32 v134, v12, v13
	s_add_u32 s98, s98, 0xc000
	s_addc_u32 s99, s99, 0
	v_mov_b32_dpp v135, v133 quad_perm:[1,0,3,2] row_mask:0xf bank_mask:0xf
	v_mov_b32_dpp v136, v134 quad_perm:[1,0,3,2] row_mask:0xf bank_mask:0xf
	v_perm_b32 v137, v135, v133, v131
	v_perm_b32 v138, v136, v134, v131
	global_store_dword v130, v137, s[98:99] nt
	global_store_dword v130, v138, s[98:99] offset:256 nt
	v_max_f32_e32 v46, 0, v46
	v_max_f32_e32 v47, 0, v47
	v_max_f32_e32 v14, 0, v14
	v_max_f32_e32 v15, 0, v15
	v_pk_mul_f32 v[46:47], v[46:47], v[46:47]
	v_pk_mul_f32 v[14:15], v[14:15], v[14:15]
	v_cvt_pk_bf16_f32 v139, v46, v47
	v_cvt_pk_bf16_f32 v140, v14, v15
	s_add_u32 s98, s98, 0x4000
	s_addc_u32 s99, s99, 0
	v_mov_b32_dpp v141, v139 quad_perm:[1,0,3,2] row_mask:0xf bank_mask:0xf
	v_mov_b32_dpp v142, v140 quad_perm:[1,0,3,2] row_mask:0xf bank_mask:0xf
	v_perm_b32 v143, v141, v139, v131
	v_perm_b32 v144, v142, v140, v131
	global_store_dword v130, v143, s[98:99] nt
	global_store_dword v130, v144, s[98:99] offset:256 nt
